# GEMM main loops: drop the redundant post-barrier lgkmcnt wait and the mid-segment priority flip, raise priority before the pre-MMA barrier, lower it after the post-MMA barrier (fewer issue slots on th
# baseline (speedup 1.0000x reference)
.LBB0_117:
	s_add_u32 s2, s0, 0xfff80080
	s_addc_u32 s3, s1, -1
	s_add_i32 s27, 0, 0x10000
	s_cmp_eq_u32 s47, 28
	s_cselect_b32 s29, s17, s3
	s_cselect_b32 s28, s43, s2
	v_add_u32_e32 v0, s27, v171
	s_cselect_b32 s3, s19, s46
	s_cselect_b32 s2, s44, s45
	s_add_i32 s33, 0, 0x14000
	ds_read_b128 v[130:133], v0
	ds_read_b128 v[134:137], v0 offset:1024
	ds_read_b128 v[154:157], v0 offset:2048
	ds_read_b128 v[158:161], v0 offset:3072
	v_add_u32_e32 v0, s33, v171
	ds_read_b128 v[162:165], v0
	ds_read_b128 v[166:169], v0 offset:1024
	ds_read_b128 v[176:179], v0 offset:2048
	ds_read_b128 v[180:183], v0 offset:3072
	v_lshl_add_u64 v[240:241], s[0:1], 0, v[150:151]
	s_add_i32 m0, s67, 0xc000
	ds_read_b128 v[184:187], v175
	ds_read_b128 v[188:191], v175 offset:1024
	ds_read_b128 v[192:195], v175 offset:2048
	ds_read_b128 v[196:199], v175 offset:3072
	ds_read_b128 v[224:227], v175 offset:4096
	ds_read_b128 v[228:231], v175 offset:5120
	ds_read_b128 v[232:235], v175 offset:6144
	ds_read_b128 v[236:239], v175 offset:7168
	global_load_lds_dwordx4 v[240:241], off
	v_lshl_add_u64 v[240:241], s[0:1], 0, v[152:153]
	s_add_i32 m0, s67, 0xe000
	s_nop 0
	global_load_lds_dwordx4 v[240:241], off
	s_waitcnt vmcnt(8)
	s_waitcnt lgkmcnt(0)
	s_setprio 1
	s_barrier
	v_mfma_f32_16x16x32_bf16 v[126:129], v[130:133], v[184:187], v[126:129]
	v_mfma_f32_16x16x32_bf16 v[122:125], v[154:157], v[184:187], v[122:125]
	v_mfma_f32_16x16x32_bf16 v[110:113], v[130:133], v[192:195], v[110:113]
	v_mfma_f32_16x16x32_bf16 v[106:109], v[154:157], v[192:195], v[106:109]
	v_mfma_f32_16x16x32_bf16 v[94:97], v[130:133], v[224:227], v[94:97]
	v_mfma_f32_16x16x32_bf16 v[90:93], v[154:157], v[224:227], v[90:93]
	v_mfma_f32_16x16x32_bf16 v[78:81], v[130:133], v[232:235], v[78:81]
	v_mfma_f32_16x16x32_bf16 v[74:77], v[154:157], v[232:235], v[74:77]
	v_mfma_f32_16x16x32_bf16 v[126:129], v[134:137], v[188:191], v[126:129]
	v_mfma_f32_16x16x32_bf16 v[122:125], v[158:161], v[188:191], v[122:125]
	v_mfma_f32_16x16x32_bf16 v[110:113], v[134:137], v[196:199], v[110:113]
	v_mfma_f32_16x16x32_bf16 v[106:109], v[158:161], v[196:199], v[106:109]
	v_mfma_f32_16x16x32_bf16 v[94:97], v[134:137], v[228:231], v[94:97]
	v_mfma_f32_16x16x32_bf16 v[90:93], v[158:161], v[228:231], v[90:93]
	v_mfma_f32_16x16x32_bf16 v[78:81], v[134:137], v[236:239], v[78:81]
	v_mfma_f32_16x16x32_bf16 v[74:77], v[158:161], v[236:239], v[74:77]
	v_mfma_f32_16x16x32_bf16 v[118:121], v[162:165], v[184:187], v[118:121]
	v_mfma_f32_16x16x32_bf16 v[114:117], v[176:179], v[184:187], v[114:117]
	v_mfma_f32_16x16x32_bf16 v[102:105], v[162:165], v[192:195], v[102:105]
	v_mfma_f32_16x16x32_bf16 v[98:101], v[176:179], v[192:195], v[98:101]
	v_mfma_f32_16x16x32_bf16 v[86:89], v[162:165], v[224:227], v[86:89]
	v_mfma_f32_16x16x32_bf16 v[82:85], v[176:179], v[224:227], v[82:85]
	v_mfma_f32_16x16x32_bf16 v[70:73], v[162:165], v[232:235], v[70:73]
	v_mfma_f32_16x16x32_bf16 v[66:69], v[176:179], v[232:235], v[66:69]
	v_mfma_f32_16x16x32_bf16 v[118:121], v[166:169], v[188:191], v[118:121]
	v_mfma_f32_16x16x32_bf16 v[114:117], v[180:183], v[188:191], v[114:117]
	v_mfma_f32_16x16x32_bf16 v[102:105], v[166:169], v[196:199], v[102:105]
	v_mfma_f32_16x16x32_bf16 v[98:101], v[180:183], v[196:199], v[98:101]
	v_mfma_f32_16x16x32_bf16 v[86:89], v[166:169], v[228:231], v[86:89]
	v_mfma_f32_16x16x32_bf16 v[82:85], v[180:183], v[228:231], v[82:85]
	v_mfma_f32_16x16x32_bf16 v[70:73], v[166:169], v[236:239], v[70:73]
	v_mfma_f32_16x16x32_bf16 v[66:69], v[180:183], v[236:239], v[66:69]
	s_barrier
	s_setprio 0
	s_add_i32 s27, s27, s64
	v_lshl_add_u64 v[240:241], s[2:3], 0, v[142:143]
	s_mov_b32 m0, s27
	ds_read_b128 v[184:187], v175 offset:16384
	ds_read_b128 v[188:191], v175 offset:17408
	ds_read_b128 v[192:195], v175 offset:18432
	ds_read_b128 v[196:199], v175 offset:19456
	ds_read_b128 v[224:227], v175 offset:20480
	ds_read_b128 v[228:231], v175 offset:21504
	ds_read_b128 v[232:235], v175 offset:22528
	ds_read_b128 v[236:239], v175 offset:23552
	global_load_lds_dwordx4 v[240:241], off
	s_add_i32 m0, s27, 0x2000
	s_add_u32 s48, s2, 0x80000
	v_lshl_add_u64 v[242:243], s[2:3], 0, v[138:139]
	s_addc_u32 s49, s3, 0
	s_add_i32 s27, s33, s64
	global_load_lds_dwordx4 v[242:243], off
	v_lshl_add_u64 v[244:245], s[48:49], 0, v[142:143]
	s_mov_b32 m0, s27
	v_lshl_add_u64 v[246:247], s[28:29], 0, v[140:141]
	global_load_lds_dwordx4 v[244:245], off
	v_lshl_add_u64 v[244:245], s[48:49], 0, v[138:139]
	s_add_i32 m0, s27, 0x2000
	s_nop 0
	global_load_lds_dwordx4 v[244:245], off
	v_lshl_add_u64 v[244:245], s[28:29], 0, v[144:145]
	s_mov_b32 m0, s67
	s_nop 0
	global_load_lds_dwordx4 v[244:245], off
	s_mov_b32 m0, s68
	s_nop 0
	global_load_lds_dwordx4 v[246:247], off
	s_waitcnt vmcnt(8)
	s_waitcnt lgkmcnt(0)
	s_setprio 1
	s_barrier
	v_mfma_f32_16x16x32_bf16 v[62:65], v[130:133], v[184:187], v[62:65]
	v_mfma_f32_16x16x32_bf16 v[58:61], v[154:157], v[184:187], v[58:61]
	v_mfma_f32_16x16x32_bf16 v[46:49], v[130:133], v[192:195], v[46:49]
	v_mfma_f32_16x16x32_bf16 v[42:45], v[154:157], v[192:195], v[42:45]
	v_mfma_f32_16x16x32_bf16 v[30:33], v[130:133], v[224:227], v[30:33]
	v_mfma_f32_16x16x32_bf16 v[26:29], v[154:157], v[224:227], v[26:29]
	v_mfma_f32_16x16x32_bf16 v[14:17], v[130:133], v[232:235], v[14:17]
	v_mfma_f32_16x16x32_bf16 v[10:13], v[154:157], v[232:235], v[10:13]
	v_mfma_f32_16x16x32_bf16 v[62:65], v[134:137], v[188:191], v[62:65]
	v_mfma_f32_16x16x32_bf16 v[58:61], v[158:161], v[188:191], v[58:61]
	v_mfma_f32_16x16x32_bf16 v[46:49], v[134:137], v[196:199], v[46:49]
	v_mfma_f32_16x16x32_bf16 v[42:45], v[158:161], v[196:199], v[42:45]
	v_mfma_f32_16x16x32_bf16 v[30:33], v[134:137], v[228:231], v[30:33]
	v_mfma_f32_16x16x32_bf16 v[26:29], v[158:161], v[228:231], v[26:29]
	v_mfma_f32_16x16x32_bf16 v[14:17], v[134:137], v[236:239], v[14:17]
	v_mfma_f32_16x16x32_bf16 v[10:13], v[158:161], v[236:239], v[10:13]
	v_mfma_f32_16x16x32_bf16 v[54:57], v[162:165], v[184:187], v[54:57]
	v_mfma_f32_16x16x32_bf16 v[50:53], v[176:179], v[184:187], v[50:53]
	v_mfma_f32_16x16x32_bf16 v[38:41], v[162:165], v[192:195], v[38:41]
	v_mfma_f32_16x16x32_bf16 v[34:37], v[176:179], v[192:195], v[34:37]
	v_mfma_f32_16x16x32_bf16 v[22:25], v[162:165], v[224:227], v[22:25]
	v_mfma_f32_16x16x32_bf16 v[18:21], v[176:179], v[224:227], v[18:21]
	v_mfma_f32_16x16x32_bf16 v[6:9], v[162:165], v[232:235], v[6:9]
	v_mfma_f32_16x16x32_bf16 v[2:5], v[176:179], v[232:235], v[2:5]
	v_mfma_f32_16x16x32_bf16 v[54:57], v[166:169], v[188:191], v[54:57]
	v_mfma_f32_16x16x32_bf16 v[50:53], v[180:183], v[188:191], v[50:53]
	v_mfma_f32_16x16x32_bf16 v[38:41], v[166:169], v[196:199], v[38:41]
	v_mfma_f32_16x16x32_bf16 v[34:37], v[180:183], v[196:199], v[34:37]
	v_mfma_f32_16x16x32_bf16 v[22:25], v[166:169], v[228:231], v[22:25]
	v_mfma_f32_16x16x32_bf16 v[18:21], v[180:183], v[228:231], v[18:21]
	v_mfma_f32_16x16x32_bf16 v[6:9], v[166:169], v[236:239], v[6:9]
	v_mfma_f32_16x16x32_bf16 v[2:5], v[180:183], v[236:239], v[2:5]
	s_barrier
	s_setprio 0
	s_add_i32 s27, 0, 0x18000
	v_add_u32_e32 v0, s27, v171
	s_add_i32 s33, 0, 0x1c000
	ds_read_b128 v[130:133], v0
	ds_read_b128 v[134:137], v0 offset:1024
	ds_read_b128 v[154:157], v0 offset:2048
	ds_read_b128 v[158:161], v0 offset:3072
	v_add_u32_e32 v0, s33, v171
	ds_read_b128 v[162:165], v0
	ds_read_b128 v[166:169], v0 offset:1024
	ds_read_b128 v[176:179], v0 offset:2048
	ds_read_b128 v[180:183], v0 offset:3072
	s_add_u32 s28, s28, 0x80000
	s_addc_u32 s29, s29, 0
	s_mov_b32 m0, s69
	v_lshl_add_u64 v[248:249], s[28:29], 0, v[144:145]
	ds_read_b128 v[184:187], v175 offset:32768
	ds_read_b128 v[188:191], v175 offset:33792
	ds_read_b128 v[192:195], v175 offset:34816
	ds_read_b128 v[196:199], v175 offset:35840
	ds_read_b128 v[224:227], v175 offset:36864
	ds_read_b128 v[228:231], v175 offset:37888
	ds_read_b128 v[232:235], v175 offset:38912
	ds_read_b128 v[236:239], v175 offset:39936
	global_load_lds_dwordx4 v[248:249], off
	v_lshl_add_u64 v[248:249], s[28:29], 0, v[140:141]
	s_mov_b32 m0, s70
	s_nop 0
	global_load_lds_dwordx4 v[248:249], off
	s_waitcnt vmcnt(8)
	s_waitcnt lgkmcnt(0)
	s_setprio 1
	s_barrier
	v_mfma_f32_16x16x32_bf16 v[126:129], v[130:133], v[184:187], v[126:129]
	v_mfma_f32_16x16x32_bf16 v[122:125], v[154:157], v[184:187], v[122:125]
	v_mfma_f32_16x16x32_bf16 v[110:113], v[130:133], v[192:195], v[110:113]
	v_mfma_f32_16x16x32_bf16 v[106:109], v[154:157], v[192:195], v[106:109]
	v_mfma_f32_16x16x32_bf16 v[94:97], v[130:133], v[224:227], v[94:97]
	v_mfma_f32_16x16x32_bf16 v[90:93], v[154:157], v[224:227], v[90:93]
	v_mfma_f32_16x16x32_bf16 v[78:81], v[130:133], v[232:235], v[78:81]
	v_mfma_f32_16x16x32_bf16 v[74:77], v[154:157], v[232:235], v[74:77]
	v_mfma_f32_16x16x32_bf16 v[126:129], v[134:137], v[188:191], v[126:129]
	v_mfma_f32_16x16x32_bf16 v[122:125], v[158:161], v[188:191], v[122:125]
	v_mfma_f32_16x16x32_bf16 v[110:113], v[134:137], v[196:199], v[110:113]
	v_mfma_f32_16x16x32_bf16 v[106:109], v[158:161], v[196:199], v[106:109]
	v_mfma_f32_16x16x32_bf16 v[94:97], v[134:137], v[228:231], v[94:97]
	v_mfma_f32_16x16x32_bf16 v[90:93], v[158:161], v[228:231], v[90:93]
	v_mfma_f32_16x16x32_bf16 v[78:81], v[134:137], v[236:239], v[78:81]
	v_mfma_f32_16x16x32_bf16 v[74:77], v[158:161], v[236:239], v[74:77]
	v_mfma_f32_16x16x32_bf16 v[118:121], v[162:165], v[184:187], v[118:121]
	v_mfma_f32_16x16x32_bf16 v[114:117], v[176:179], v[184:187], v[114:117]
	v_mfma_f32_16x16x32_bf16 v[102:105], v[162:165], v[192:195], v[102:105]
	v_mfma_f32_16x16x32_bf16 v[98:101], v[176:179], v[192:195], v[98:101]
	v_mfma_f32_16x16x32_bf16 v[86:89], v[162:165], v[224:227], v[86:89]
	v_mfma_f32_16x16x32_bf16 v[82:85], v[176:179], v[224:227], v[82:85]
	v_mfma_f32_16x16x32_bf16 v[70:73], v[162:165], v[232:235], v[70:73]
	v_mfma_f32_16x16x32_bf16 v[66:69], v[176:179], v[232:235], v[66:69]
	v_mfma_f32_16x16x32_bf16 v[118:121], v[166:169], v[188:191], v[118:121]
	v_mfma_f32_16x16x32_bf16 v[114:117], v[180:183], v[188:191], v[114:117]
	v_mfma_f32_16x16x32_bf16 v[102:105], v[166:169], v[196:199], v[102:105]
	v_mfma_f32_16x16x32_bf16 v[98:101], v[180:183], v[196:199], v[98:101]
	v_mfma_f32_16x16x32_bf16 v[86:89], v[166:169], v[228:231], v[86:89]
	v_mfma_f32_16x16x32_bf16 v[82:85], v[180:183], v[228:231], v[82:85]
	v_mfma_f32_16x16x32_bf16 v[70:73], v[166:169], v[236:239], v[70:73]
	v_mfma_f32_16x16x32_bf16 v[66:69], v[180:183], v[236:239], v[66:69]
	s_barrier
	s_setprio 0
	s_add_i32 s27, s27, s64
	v_lshl_add_u64 v[240:241], v[240:241], 0, s[30:31]
	s_mov_b32 m0, s27
	ds_read_b128 v[184:187], v175 offset:49152
	ds_read_b128 v[188:191], v175 offset:50176
	ds_read_b128 v[192:195], v175 offset:51200
	ds_read_b128 v[196:199], v175 offset:52224
	ds_read_b128 v[224:227], v175 offset:53248
	ds_read_b128 v[228:231], v175 offset:54272
	ds_read_b128 v[232:235], v175 offset:55296
	ds_read_b128 v[236:239], v175 offset:56320
	global_load_lds_dwordx4 v[240:241], off
	s_add_i32 m0, s27, 0x2000
	s_add_u32 s2, s2, 0x80080
	v_lshl_add_u64 v[240:241], v[242:243], 0, s[30:31]
	s_addc_u32 s3, s3, 0
	s_add_i32 s27, s33, s64
	global_load_lds_dwordx4 v[240:241], off
	v_lshl_add_u64 v[240:241], s[2:3], 0, v[142:143]
	s_mov_b32 m0, s27
	s_nop 0
	global_load_lds_dwordx4 v[240:241], off
	v_lshl_add_u64 v[240:241], s[2:3], 0, v[138:139]
	s_add_i32 m0, s27, 0x2000
	s_nop 0
	global_load_lds_dwordx4 v[240:241], off
	v_lshl_add_u64 v[240:241], v[244:245], 0, s[30:31]
	s_mov_b32 m0, s72
	s_nop 0
	global_load_lds_dwordx4 v[240:241], off
	v_lshl_add_u64 v[240:241], v[246:247], 0, s[30:31]
	s_mov_b32 m0, s73
	s_nop 0
	global_load_lds_dwordx4 v[240:241], off
	s_waitcnt vmcnt(8)
	s_waitcnt lgkmcnt(0)
	s_setprio 1
	s_barrier
	v_mfma_f32_16x16x32_bf16 v[62:65], v[130:133], v[184:187], v[62:65]
	v_mfma_f32_16x16x32_bf16 v[58:61], v[154:157], v[184:187], v[58:61]
	v_mfma_f32_16x16x32_bf16 v[46:49], v[130:133], v[192:195], v[46:49]
	v_mfma_f32_16x16x32_bf16 v[42:45], v[154:157], v[192:195], v[42:45]
	v_mfma_f32_16x16x32_bf16 v[30:33], v[130:133], v[224:227], v[30:33]
	v_mfma_f32_16x16x32_bf16 v[26:29], v[154:157], v[224:227], v[26:29]
	v_mfma_f32_16x16x32_bf16 v[14:17], v[130:133], v[232:235], v[14:17]
	v_mfma_f32_16x16x32_bf16 v[10:13], v[154:157], v[232:235], v[10:13]
	v_mfma_f32_16x16x32_bf16 v[62:65], v[134:137], v[188:191], v[62:65]
	v_mfma_f32_16x16x32_bf16 v[58:61], v[158:161], v[188:191], v[58:61]
	v_mfma_f32_16x16x32_bf16 v[46:49], v[134:137], v[196:199], v[46:49]
	v_mfma_f32_16x16x32_bf16 v[42:45], v[158:161], v[196:199], v[42:45]
	v_mfma_f32_16x16x32_bf16 v[30:33], v[134:137], v[228:231], v[30:33]
	v_mfma_f32_16x16x32_bf16 v[26:29], v[158:161], v[228:231], v[26:29]
	v_mfma_f32_16x16x32_bf16 v[14:17], v[134:137], v[236:239], v[14:17]
	v_mfma_f32_16x16x32_bf16 v[10:13], v[158:161], v[236:239], v[10:13]
	v_mfma_f32_16x16x32_bf16 v[54:57], v[162:165], v[184:187], v[54:57]
	v_mfma_f32_16x16x32_bf16 v[50:53], v[176:179], v[184:187], v[50:53]
	v_mfma_f32_16x16x32_bf16 v[38:41], v[162:165], v[192:195], v[38:41]
	v_mfma_f32_16x16x32_bf16 v[34:37], v[176:179], v[192:195], v[34:37]
	v_mfma_f32_16x16x32_bf16 v[22:25], v[162:165], v[224:227], v[22:25]
	v_mfma_f32_16x16x32_bf16 v[18:21], v[176:179], v[224:227], v[18:21]
	v_mfma_f32_16x16x32_bf16 v[6:9], v[162:165], v[232:235], v[6:9]
	v_mfma_f32_16x16x32_bf16 v[2:5], v[176:179], v[232:235], v[2:5]
	v_mfma_f32_16x16x32_bf16 v[54:57], v[166:169], v[188:191], v[54:57]
	v_mfma_f32_16x16x32_bf16 v[50:53], v[180:183], v[188:191], v[50:53]
	v_mfma_f32_16x16x32_bf16 v[38:41], v[166:169], v[196:199], v[38:41]
	v_mfma_f32_16x16x32_bf16 v[34:37], v[180:183], v[196:199], v[34:37]
	v_mfma_f32_16x16x32_bf16 v[22:25], v[166:169], v[228:231], v[22:25]
	v_mfma_f32_16x16x32_bf16 v[18:21], v[180:183], v[228:231], v[18:21]
	v_mfma_f32_16x16x32_bf16 v[6:9], v[166:169], v[236:239], v[6:9]
	v_mfma_f32_16x16x32_bf16 v[2:5], v[180:183], v[236:239], v[2:5]
	s_barrier
	s_setprio 0
	s_add_i32 s47, s47, 2
	s_add_u32 s0, s0, 0x100
	s_addc_u32 s1, s1, 0
	s_add_u32 s45, s45, 0x100
	s_addc_u32 s46, s46, 0
	s_cmp_gt_u32 s47, 29
	s_cbranch_scc0 .LBB0_117
	s_and_b64 vcc, exec, s[12:13]
	s_cbranch_vccz .LBB0_120
	s_barrier

.LBB0_850:
	s_add_u32 s16, s2, 0xfffc0080
	s_addc_u32 s17, s3, -1
	s_add_i32 s27, 0, 0x10000
	s_cmp_eq_u32 s49, 12
	s_cselect_b32 s19, s11, s17
	s_cselect_b32 s18, s45, s16
	v_add_u32_e32 v144, s27, v147
	s_cselect_b32 s17, s9, s48
	s_cselect_b32 s16, s46, s47
	s_add_i32 s33, 0, 0x14000
	ds_read_b128 v[140:143], v144
	ds_read_b128 v[150:153], v144 offset:1024
	ds_read_b128 v[154:157], v144 offset:2048
	ds_read_b128 v[158:161], v144 offset:3072
	v_add_u32_e32 v144, s33, v147
	ds_read_b128 v[162:165], v144
	ds_read_b128 v[166:169], v144 offset:1024
	ds_read_b128 v[170:173], v144 offset:2048
	ds_read_b128 v[174:177], v144 offset:3072
	v_lshl_add_u64 v[144:145], s[2:3], 0, v[136:137]
	s_add_i32 m0, s29, 0xc000
	ds_read_b128 v[178:181], v149
	ds_read_b128 v[182:185], v149 offset:1024
	ds_read_b128 v[186:189], v149 offset:2048
	ds_read_b128 v[190:193], v149 offset:3072
	ds_read_b128 v[194:197], v149 offset:4096
	ds_read_b128 v[224:227], v149 offset:5120
	ds_read_b128 v[228:231], v149 offset:6144
	ds_read_b128 v[232:235], v149 offset:7168
	global_load_lds_dwordx4 v[144:145], off
	v_lshl_add_u64 v[144:145], s[2:3], 0, v[138:139]
	s_add_i32 m0, s29, 0xe000
	s_nop 0
	global_load_lds_dwordx4 v[144:145], off
	s_waitcnt vmcnt(8)
	s_waitcnt lgkmcnt(0)
	s_setprio 1
	s_barrier
	v_mfma_f32_16x16x32_bf16 v[126:129], v[140:143], v[178:181], v[126:129]
	v_mfma_f32_16x16x32_bf16 v[122:125], v[154:157], v[178:181], v[122:125]
	v_mfma_f32_16x16x32_bf16 v[110:113], v[140:143], v[186:189], v[110:113]
	v_mfma_f32_16x16x32_bf16 v[106:109], v[154:157], v[186:189], v[106:109]
	v_mfma_f32_16x16x32_bf16 v[94:97], v[140:143], v[194:197], v[94:97]
	v_mfma_f32_16x16x32_bf16 v[90:93], v[154:157], v[194:197], v[90:93]
	v_mfma_f32_16x16x32_bf16 v[78:81], v[140:143], v[228:231], v[78:81]
	v_mfma_f32_16x16x32_bf16 v[74:77], v[154:157], v[228:231], v[74:77]
	v_mfma_f32_16x16x32_bf16 v[126:129], v[150:153], v[182:185], v[126:129]
	v_mfma_f32_16x16x32_bf16 v[122:125], v[158:161], v[182:185], v[122:125]
	v_mfma_f32_16x16x32_bf16 v[110:113], v[150:153], v[190:193], v[110:113]
	v_mfma_f32_16x16x32_bf16 v[106:109], v[158:161], v[190:193], v[106:109]
	v_mfma_f32_16x16x32_bf16 v[94:97], v[150:153], v[224:227], v[94:97]
	v_mfma_f32_16x16x32_bf16 v[90:93], v[158:161], v[224:227], v[90:93]
	v_mfma_f32_16x16x32_bf16 v[78:81], v[150:153], v[232:235], v[78:81]
	v_mfma_f32_16x16x32_bf16 v[74:77], v[158:161], v[232:235], v[74:77]
	v_mfma_f32_16x16x32_bf16 v[118:121], v[162:165], v[178:181], v[118:121]
	v_mfma_f32_16x16x32_bf16 v[114:117], v[170:173], v[178:181], v[114:117]
	v_mfma_f32_16x16x32_bf16 v[102:105], v[162:165], v[186:189], v[102:105]
	v_mfma_f32_16x16x32_bf16 v[98:101], v[170:173], v[186:189], v[98:101]
	v_mfma_f32_16x16x32_bf16 v[86:89], v[162:165], v[194:197], v[86:89]
	v_mfma_f32_16x16x32_bf16 v[82:85], v[170:173], v[194:197], v[82:85]
	v_mfma_f32_16x16x32_bf16 v[70:73], v[162:165], v[228:231], v[70:73]
	v_mfma_f32_16x16x32_bf16 v[66:69], v[170:173], v[228:231], v[66:69]
	v_mfma_f32_16x16x32_bf16 v[118:121], v[166:169], v[182:185], v[118:121]
	v_mfma_f32_16x16x32_bf16 v[114:117], v[174:177], v[182:185], v[114:117]
	v_mfma_f32_16x16x32_bf16 v[102:105], v[166:169], v[190:193], v[102:105]
	v_mfma_f32_16x16x32_bf16 v[98:101], v[174:177], v[190:193], v[98:101]
	v_mfma_f32_16x16x32_bf16 v[86:89], v[166:169], v[224:227], v[86:89]
	v_mfma_f32_16x16x32_bf16 v[82:85], v[174:177], v[224:227], v[82:85]
	v_mfma_f32_16x16x32_bf16 v[70:73], v[166:169], v[232:235], v[70:73]
	v_mfma_f32_16x16x32_bf16 v[66:69], v[174:177], v[232:235], v[66:69]
	s_barrier
	s_setprio 0
	s_add_i32 s27, s27, s28
	v_lshl_add_u64 v[144:145], s[16:17], 0, v[0:1]
	s_mov_b32 m0, s27
	ds_read_b128 v[178:181], v149 offset:16384
	ds_read_b128 v[182:185], v149 offset:17408
	ds_read_b128 v[186:189], v149 offset:18432
	ds_read_b128 v[190:193], v149 offset:19456
	ds_read_b128 v[194:197], v149 offset:20480
	ds_read_b128 v[224:227], v149 offset:21504
	ds_read_b128 v[228:231], v149 offset:22528
	ds_read_b128 v[232:235], v149 offset:23552
	global_load_lds_dwordx4 v[144:145], off
	s_add_i32 m0, s27, 0x2000
	s_add_u32 s50, s16, 0x40000
	v_lshl_add_u64 v[198:199], s[16:17], 0, v[130:131]
	s_addc_u32 s51, s17, 0
	s_add_i32 s27, s33, s28
	global_load_lds_dwordx4 v[198:199], off
	v_lshl_add_u64 v[236:237], s[50:51], 0, v[0:1]
	s_mov_b32 m0, s27
	v_lshl_add_u64 v[238:239], s[18:19], 0, v[132:133]
	global_load_lds_dwordx4 v[236:237], off
	v_lshl_add_u64 v[236:237], s[50:51], 0, v[130:131]
	s_add_i32 m0, s27, 0x2000
	s_nop 0
	global_load_lds_dwordx4 v[236:237], off
	v_lshl_add_u64 v[236:237], s[18:19], 0, v[134:135]
	s_mov_b32 m0, s29
	s_nop 0
	global_load_lds_dwordx4 v[236:237], off
	s_mov_b32 m0, s36
	s_nop 0
	global_load_lds_dwordx4 v[238:239], off
	s_waitcnt vmcnt(8)
	s_waitcnt lgkmcnt(0)
	s_setprio 1
	s_barrier
	v_mfma_f32_16x16x32_bf16 v[62:65], v[140:143], v[178:181], v[62:65]
	v_mfma_f32_16x16x32_bf16 v[58:61], v[154:157], v[178:181], v[58:61]
	v_mfma_f32_16x16x32_bf16 v[46:49], v[140:143], v[186:189], v[46:49]
	v_mfma_f32_16x16x32_bf16 v[42:45], v[154:157], v[186:189], v[42:45]
	v_mfma_f32_16x16x32_bf16 v[30:33], v[140:143], v[194:197], v[30:33]
	v_mfma_f32_16x16x32_bf16 v[26:29], v[154:157], v[194:197], v[26:29]
	v_mfma_f32_16x16x32_bf16 v[14:17], v[140:143], v[228:231], v[14:17]
	v_mfma_f32_16x16x32_bf16 v[10:13], v[154:157], v[228:231], v[10:13]
	v_mfma_f32_16x16x32_bf16 v[62:65], v[150:153], v[182:185], v[62:65]
	v_mfma_f32_16x16x32_bf16 v[58:61], v[158:161], v[182:185], v[58:61]
	v_mfma_f32_16x16x32_bf16 v[46:49], v[150:153], v[190:193], v[46:49]
	v_mfma_f32_16x16x32_bf16 v[42:45], v[158:161], v[190:193], v[42:45]
	v_mfma_f32_16x16x32_bf16 v[30:33], v[150:153], v[224:227], v[30:33]
	v_mfma_f32_16x16x32_bf16 v[26:29], v[158:161], v[224:227], v[26:29]
	v_mfma_f32_16x16x32_bf16 v[14:17], v[150:153], v[232:235], v[14:17]
	v_mfma_f32_16x16x32_bf16 v[10:13], v[158:161], v[232:235], v[10:13]
	v_mfma_f32_16x16x32_bf16 v[54:57], v[162:165], v[178:181], v[54:57]
	v_mfma_f32_16x16x32_bf16 v[50:53], v[170:173], v[178:181], v[50:53]
	v_mfma_f32_16x16x32_bf16 v[38:41], v[162:165], v[186:189], v[38:41]
	v_mfma_f32_16x16x32_bf16 v[34:37], v[170:173], v[186:189], v[34:37]
	v_mfma_f32_16x16x32_bf16 v[22:25], v[162:165], v[194:197], v[22:25]
	v_mfma_f32_16x16x32_bf16 v[18:21], v[170:173], v[194:197], v[18:21]
	v_mfma_f32_16x16x32_bf16 v[6:9], v[162:165], v[228:231], v[6:9]
	v_mfma_f32_16x16x32_bf16 v[2:5], v[170:173], v[228:231], v[2:5]
	v_mfma_f32_16x16x32_bf16 v[54:57], v[166:169], v[182:185], v[54:57]
	v_mfma_f32_16x16x32_bf16 v[50:53], v[174:177], v[182:185], v[50:53]
	v_mfma_f32_16x16x32_bf16 v[38:41], v[166:169], v[190:193], v[38:41]
	v_mfma_f32_16x16x32_bf16 v[34:37], v[174:177], v[190:193], v[34:37]
	v_mfma_f32_16x16x32_bf16 v[22:25], v[166:169], v[224:227], v[22:25]
	v_mfma_f32_16x16x32_bf16 v[18:21], v[174:177], v[224:227], v[18:21]
	v_mfma_f32_16x16x32_bf16 v[6:9], v[166:169], v[232:235], v[6:9]
	v_mfma_f32_16x16x32_bf16 v[2:5], v[174:177], v[232:235], v[2:5]
	s_barrier
	s_setprio 0
	s_add_i32 s27, 0, 0x18000
	s_add_i32 s33, 0, 0x1c000
	v_add_u32_e32 v158, s27, v147
	v_add_u32_e32 v174, s33, v147
	ds_read_b128 v[140:143], v158
	ds_read_b128 v[150:153], v158 offset:1024
	ds_read_b128 v[154:157], v158 offset:2048
	ds_read_b128 v[158:161], v158 offset:3072
	ds_read_b128 v[162:165], v174
	ds_read_b128 v[166:169], v174 offset:1024
	ds_read_b128 v[170:173], v174 offset:2048
	ds_read_b128 v[174:177], v174 offset:3072
	s_add_u32 s18, s18, 0x40000
	s_addc_u32 s19, s19, 0
	s_mov_b32 m0, s37
	v_lshl_add_u64 v[240:241], s[18:19], 0, v[134:135]
	ds_read_b128 v[178:181], v149 offset:32768
	ds_read_b128 v[182:185], v149 offset:33792
	ds_read_b128 v[186:189], v149 offset:34816
	ds_read_b128 v[190:193], v149 offset:35840
	ds_read_b128 v[194:197], v149 offset:36864
	ds_read_b128 v[224:227], v149 offset:37888
	ds_read_b128 v[228:231], v149 offset:38912
	ds_read_b128 v[232:235], v149 offset:39936
	global_load_lds_dwordx4 v[240:241], off
	v_lshl_add_u64 v[240:241], s[18:19], 0, v[132:133]
	s_mov_b32 m0, s40
	s_nop 0
	global_load_lds_dwordx4 v[240:241], off
	s_waitcnt vmcnt(8)
	s_waitcnt lgkmcnt(0)
	s_setprio 1
	s_barrier
	v_mfma_f32_16x16x32_bf16 v[126:129], v[140:143], v[178:181], v[126:129]
	v_mfma_f32_16x16x32_bf16 v[122:125], v[154:157], v[178:181], v[122:125]
	v_mfma_f32_16x16x32_bf16 v[110:113], v[140:143], v[186:189], v[110:113]
	v_mfma_f32_16x16x32_bf16 v[106:109], v[154:157], v[186:189], v[106:109]
	v_mfma_f32_16x16x32_bf16 v[94:97], v[140:143], v[194:197], v[94:97]
	v_mfma_f32_16x16x32_bf16 v[90:93], v[154:157], v[194:197], v[90:93]
	v_mfma_f32_16x16x32_bf16 v[78:81], v[140:143], v[228:231], v[78:81]
	v_mfma_f32_16x16x32_bf16 v[74:77], v[154:157], v[228:231], v[74:77]
	v_mfma_f32_16x16x32_bf16 v[126:129], v[150:153], v[182:185], v[126:129]
	v_mfma_f32_16x16x32_bf16 v[122:125], v[158:161], v[182:185], v[122:125]
	v_mfma_f32_16x16x32_bf16 v[110:113], v[150:153], v[190:193], v[110:113]
	v_mfma_f32_16x16x32_bf16 v[106:109], v[158:161], v[190:193], v[106:109]
	v_mfma_f32_16x16x32_bf16 v[94:97], v[150:153], v[224:227], v[94:97]
	v_mfma_f32_16x16x32_bf16 v[90:93], v[158:161], v[224:227], v[90:93]
	v_mfma_f32_16x16x32_bf16 v[78:81], v[150:153], v[232:235], v[78:81]
	v_mfma_f32_16x16x32_bf16 v[74:77], v[158:161], v[232:235], v[74:77]
	v_mfma_f32_16x16x32_bf16 v[118:121], v[162:165], v[178:181], v[118:121]
	v_mfma_f32_16x16x32_bf16 v[114:117], v[170:173], v[178:181], v[114:117]
	v_mfma_f32_16x16x32_bf16 v[102:105], v[162:165], v[186:189], v[102:105]
	v_mfma_f32_16x16x32_bf16 v[98:101], v[170:173], v[186:189], v[98:101]
	v_mfma_f32_16x16x32_bf16 v[86:89], v[162:165], v[194:197], v[86:89]
	v_mfma_f32_16x16x32_bf16 v[82:85], v[170:173], v[194:197], v[82:85]
	v_mfma_f32_16x16x32_bf16 v[70:73], v[162:165], v[228:231], v[70:73]
	v_mfma_f32_16x16x32_bf16 v[66:69], v[170:173], v[228:231], v[66:69]
	v_mfma_f32_16x16x32_bf16 v[118:121], v[166:169], v[182:185], v[118:121]
	v_mfma_f32_16x16x32_bf16 v[114:117], v[174:177], v[182:185], v[114:117]
	v_mfma_f32_16x16x32_bf16 v[102:105], v[166:169], v[190:193], v[102:105]
	v_mfma_f32_16x16x32_bf16 v[98:101], v[174:177], v[190:193], v[98:101]
	v_mfma_f32_16x16x32_bf16 v[86:89], v[166:169], v[224:227], v[86:89]
	v_mfma_f32_16x16x32_bf16 v[82:85], v[174:177], v[224:227], v[82:85]
	v_mfma_f32_16x16x32_bf16 v[70:73], v[166:169], v[232:235], v[70:73]
	v_mfma_f32_16x16x32_bf16 v[66:69], v[174:177], v[232:235], v[66:69]
	s_barrier
	s_setprio 0
	s_add_i32 s18, s27, s28
	v_lshl_add_u64 v[144:145], v[144:145], 0, s[30:31]
	s_mov_b32 m0, s18
	ds_read_b128 v[178:181], v149 offset:49152
	ds_read_b128 v[182:185], v149 offset:50176
	ds_read_b128 v[186:189], v149 offset:51200
	ds_read_b128 v[190:193], v149 offset:52224
	ds_read_b128 v[194:197], v149 offset:53248
	ds_read_b128 v[224:227], v149 offset:54272
	ds_read_b128 v[228:231], v149 offset:55296
	ds_read_b128 v[232:235], v149 offset:56320
	global_load_lds_dwordx4 v[144:145], off
	s_add_i32 m0, s18, 0x2000
	s_add_u32 s16, s16, 0x40080
	v_lshl_add_u64 v[144:145], v[198:199], 0, s[30:31]
	s_addc_u32 s17, s17, 0
	s_add_i32 s18, s33, s28
	global_load_lds_dwordx4 v[144:145], off
	v_lshl_add_u64 v[144:145], s[16:17], 0, v[0:1]
	s_mov_b32 m0, s18
	s_nop 0
	global_load_lds_dwordx4 v[144:145], off
	v_lshl_add_u64 v[144:145], s[16:17], 0, v[130:131]
	s_add_i32 m0, s18, 0x2000
	s_nop 0
	global_load_lds_dwordx4 v[144:145], off
	v_lshl_add_u64 v[144:145], v[236:237], 0, s[30:31]
	s_mov_b32 m0, s41
	s_nop 0
	global_load_lds_dwordx4 v[144:145], off
	v_lshl_add_u64 v[144:145], v[238:239], 0, s[30:31]
	s_mov_b32 m0, s42
	s_nop 0
	global_load_lds_dwordx4 v[144:145], off
	s_waitcnt vmcnt(8)
	s_waitcnt lgkmcnt(0)
	s_setprio 1
	s_barrier
	v_mfma_f32_16x16x32_bf16 v[62:65], v[140:143], v[178:181], v[62:65]
	v_mfma_f32_16x16x32_bf16 v[58:61], v[154:157], v[178:181], v[58:61]
	v_mfma_f32_16x16x32_bf16 v[46:49], v[140:143], v[186:189], v[46:49]
	v_mfma_f32_16x16x32_bf16 v[42:45], v[154:157], v[186:189], v[42:45]
	v_mfma_f32_16x16x32_bf16 v[30:33], v[140:143], v[194:197], v[30:33]
	v_mfma_f32_16x16x32_bf16 v[26:29], v[154:157], v[194:197], v[26:29]
	v_mfma_f32_16x16x32_bf16 v[14:17], v[140:143], v[228:231], v[14:17]
	v_mfma_f32_16x16x32_bf16 v[10:13], v[154:157], v[228:231], v[10:13]
	v_mfma_f32_16x16x32_bf16 v[62:65], v[150:153], v[182:185], v[62:65]
	v_mfma_f32_16x16x32_bf16 v[58:61], v[158:161], v[182:185], v[58:61]
	v_mfma_f32_16x16x32_bf16 v[46:49], v[150:153], v[190:193], v[46:49]
	v_mfma_f32_16x16x32_bf16 v[42:45], v[158:161], v[190:193], v[42:45]
	v_mfma_f32_16x16x32_bf16 v[30:33], v[150:153], v[224:227], v[30:33]
	v_mfma_f32_16x16x32_bf16 v[26:29], v[158:161], v[224:227], v[26:29]
	v_mfma_f32_16x16x32_bf16 v[14:17], v[150:153], v[232:235], v[14:17]
	v_mfma_f32_16x16x32_bf16 v[10:13], v[158:161], v[232:235], v[10:13]
	v_mfma_f32_16x16x32_bf16 v[54:57], v[162:165], v[178:181], v[54:57]
	v_mfma_f32_16x16x32_bf16 v[50:53], v[170:173], v[178:181], v[50:53]
	v_mfma_f32_16x16x32_bf16 v[38:41], v[162:165], v[186:189], v[38:41]
	v_mfma_f32_16x16x32_bf16 v[34:37], v[170:173], v[186:189], v[34:37]
	v_mfma_f32_16x16x32_bf16 v[22:25], v[162:165], v[194:197], v[22:25]
	v_mfma_f32_16x16x32_bf16 v[18:21], v[170:173], v[194:197], v[18:21]
	v_mfma_f32_16x16x32_bf16 v[6:9], v[162:165], v[228:231], v[6:9]
	v_mfma_f32_16x16x32_bf16 v[2:5], v[170:173], v[228:231], v[2:5]
	v_mfma_f32_16x16x32_bf16 v[54:57], v[166:169], v[182:185], v[54:57]
	v_mfma_f32_16x16x32_bf16 v[50:53], v[174:177], v[182:185], v[50:53]
	v_mfma_f32_16x16x32_bf16 v[38:41], v[166:169], v[190:193], v[38:41]
	v_mfma_f32_16x16x32_bf16 v[34:37], v[174:177], v[190:193], v[34:37]
	v_mfma_f32_16x16x32_bf16 v[22:25], v[166:169], v[224:227], v[22:25]
	v_mfma_f32_16x16x32_bf16 v[18:21], v[174:177], v[224:227], v[18:21]
	v_mfma_f32_16x16x32_bf16 v[6:9], v[166:169], v[232:235], v[6:9]
	v_mfma_f32_16x16x32_bf16 v[2:5], v[174:177], v[232:235], v[2:5]
	s_barrier
	s_setprio 0
	s_add_i32 s49, s49, 2
	s_add_u32 s2, s2, 0x100
	s_addc_u32 s3, s3, 0
	s_add_u32 s47, s47, 0x100
	s_addc_u32 s48, s48, 0
	s_cmp_gt_u32 s49, 13
	s_cbranch_scc0 .LBB0_850
	s_and_b64 vcc, exec, s[6:7]
	s_cbranch_vccz .LBB0_853
	s_barrier

.LBB0_922:
	s_add_u32 s14, s2, 0xfffc0080
	s_addc_u32 s15, s3, -1
	s_add_i32 s27, 0, 0x10000
	s_cmp_eq_u32 s51, 12
	s_cselect_b32 s17, s9, s15
	s_cselect_b32 s16, s43, s14
	v_add_u32_e32 v148, s27, v151
	s_cselect_b32 s15, s7, s50
	s_cselect_b32 s14, s48, s49
	s_add_i32 s33, 0, 0x14000
	ds_read_b128 v[140:143], v148
	ds_read_b128 v[144:147], v148 offset:1024
	ds_read_b128 v[162:165], v148 offset:2048
	ds_read_b128 v[166:169], v148 offset:3072
	v_add_u32_e32 v148, s33, v151
	ds_read_b128 v[170:173], v148
	ds_read_b128 v[174:177], v148 offset:1024
	ds_read_b128 v[178:181], v148 offset:2048
	ds_read_b128 v[182:185], v148 offset:3072
	v_lshl_add_u64 v[148:149], s[2:3], 0, v[136:137]
	s_add_i32 m0, s21, 0xc000
	ds_read_b128 v[186:189], v160
	ds_read_b128 v[190:193], v160 offset:1024
	ds_read_b128 v[194:197], v160 offset:2048
	ds_read_b128 v[224:227], v160 offset:3072
	ds_read_b128 v[228:231], v160 offset:4096
	ds_read_b128 v[232:235], v160 offset:5120
	ds_read_b128 v[236:239], v160 offset:6144
	ds_read_b128 v[240:243], v160 offset:7168
	global_load_lds_dwordx4 v[148:149], off
	v_lshl_add_u64 v[148:149], s[2:3], 0, v[138:139]
	s_add_i32 m0, s21, 0xe000
	s_nop 0
	global_load_lds_dwordx4 v[148:149], off
	s_waitcnt vmcnt(8)
	s_waitcnt lgkmcnt(0)
	s_setprio 1
	s_barrier
	v_mfma_f32_16x16x32_bf16 v[126:129], v[140:143], v[186:189], v[126:129]
	v_mfma_f32_16x16x32_bf16 v[122:125], v[162:165], v[186:189], v[122:125]
	v_mfma_f32_16x16x32_bf16 v[118:121], v[140:143], v[194:197], v[118:121]
	v_mfma_f32_16x16x32_bf16 v[114:117], v[162:165], v[194:197], v[114:117]
	v_mfma_f32_16x16x32_bf16 v[110:113], v[140:143], v[228:231], v[110:113]
	v_mfma_f32_16x16x32_bf16 v[106:109], v[162:165], v[228:231], v[106:109]
	v_mfma_f32_16x16x32_bf16 v[102:105], v[140:143], v[236:239], v[102:105]
	v_mfma_f32_16x16x32_bf16 v[98:101], v[162:165], v[236:239], v[98:101]
	v_mfma_f32_16x16x32_bf16 v[126:129], v[144:147], v[190:193], v[126:129]
	v_mfma_f32_16x16x32_bf16 v[122:125], v[166:169], v[190:193], v[122:125]
	v_mfma_f32_16x16x32_bf16 v[118:121], v[144:147], v[224:227], v[118:121]
	v_mfma_f32_16x16x32_bf16 v[114:117], v[166:169], v[224:227], v[114:117]
	v_mfma_f32_16x16x32_bf16 v[110:113], v[144:147], v[232:235], v[110:113]
	v_mfma_f32_16x16x32_bf16 v[106:109], v[166:169], v[232:235], v[106:109]
	v_mfma_f32_16x16x32_bf16 v[102:105], v[144:147], v[240:243], v[102:105]
	v_mfma_f32_16x16x32_bf16 v[98:101], v[166:169], v[240:243], v[98:101]
	v_mfma_f32_16x16x32_bf16 v[94:97], v[170:173], v[186:189], v[94:97]
	v_mfma_f32_16x16x32_bf16 v[90:93], v[178:181], v[186:189], v[90:93]
	v_mfma_f32_16x16x32_bf16 v[86:89], v[170:173], v[194:197], v[86:89]
	v_mfma_f32_16x16x32_bf16 v[82:85], v[178:181], v[194:197], v[82:85]
	v_mfma_f32_16x16x32_bf16 v[78:81], v[170:173], v[228:231], v[78:81]
	v_mfma_f32_16x16x32_bf16 v[74:77], v[178:181], v[228:231], v[74:77]
	v_mfma_f32_16x16x32_bf16 v[70:73], v[170:173], v[236:239], v[70:73]
	v_mfma_f32_16x16x32_bf16 v[66:69], v[178:181], v[236:239], v[66:69]
	v_mfma_f32_16x16x32_bf16 v[94:97], v[174:177], v[190:193], v[94:97]
	v_mfma_f32_16x16x32_bf16 v[90:93], v[182:185], v[190:193], v[90:93]
	v_mfma_f32_16x16x32_bf16 v[86:89], v[174:177], v[224:227], v[86:89]
	v_mfma_f32_16x16x32_bf16 v[82:85], v[182:185], v[224:227], v[82:85]
	v_mfma_f32_16x16x32_bf16 v[78:81], v[174:177], v[232:235], v[78:81]
	v_mfma_f32_16x16x32_bf16 v[74:77], v[182:185], v[232:235], v[74:77]
	v_mfma_f32_16x16x32_bf16 v[70:73], v[174:177], v[240:243], v[70:73]
	v_mfma_f32_16x16x32_bf16 v[66:69], v[182:185], v[240:243], v[66:69]
	s_barrier
	s_setprio 0
	s_add_i32 s27, s27, s20
	v_lshl_add_u64 v[148:149], s[14:15], 0, v[0:1]
	s_mov_b32 m0, s27
	ds_read_b128 v[186:189], v160 offset:16384
	ds_read_b128 v[190:193], v160 offset:17408
	ds_read_b128 v[194:197], v160 offset:18432
	ds_read_b128 v[224:227], v160 offset:19456
	ds_read_b128 v[228:231], v160 offset:20480
	ds_read_b128 v[232:235], v160 offset:21504
	ds_read_b128 v[236:239], v160 offset:22528
	ds_read_b128 v[240:243], v160 offset:23552
	global_load_lds_dwordx4 v[148:149], off
	s_add_i32 m0, s27, 0x2000
	s_add_u32 s52, s14, 0x40000
	v_lshl_add_u64 v[198:199], s[14:15], 0, v[130:131]
	s_addc_u32 s53, s15, 0
	s_add_i32 s27, s33, s20
	global_load_lds_dwordx4 v[198:199], off
	v_lshl_add_u64 v[244:245], s[52:53], 0, v[0:1]
	s_mov_b32 m0, s27
	v_lshl_add_u64 v[246:247], s[16:17], 0, v[132:133]
	global_load_lds_dwordx4 v[244:245], off
	v_lshl_add_u64 v[244:245], s[52:53], 0, v[130:131]
	s_add_i32 m0, s27, 0x2000
	s_nop 0
	global_load_lds_dwordx4 v[244:245], off
	v_lshl_add_u64 v[244:245], s[16:17], 0, v[134:135]
	s_mov_b32 m0, s21
	s_nop 0
	global_load_lds_dwordx4 v[244:245], off
	s_mov_b32 m0, s28
	s_nop 0
	global_load_lds_dwordx4 v[246:247], off
	s_waitcnt vmcnt(8)
	s_waitcnt lgkmcnt(0)
	s_setprio 1
	s_barrier
	v_mfma_f32_16x16x32_bf16 v[62:65], v[140:143], v[186:189], v[62:65]
	v_mfma_f32_16x16x32_bf16 v[58:61], v[162:165], v[186:189], v[58:61]
	v_mfma_f32_16x16x32_bf16 v[54:57], v[140:143], v[194:197], v[54:57]
	v_mfma_f32_16x16x32_bf16 v[50:53], v[162:165], v[194:197], v[50:53]
	v_mfma_f32_16x16x32_bf16 v[46:49], v[140:143], v[228:231], v[46:49]
	v_mfma_f32_16x16x32_bf16 v[42:45], v[162:165], v[228:231], v[42:45]
	v_mfma_f32_16x16x32_bf16 v[38:41], v[140:143], v[236:239], v[38:41]
	v_mfma_f32_16x16x32_bf16 v[34:37], v[162:165], v[236:239], v[34:37]
	v_mfma_f32_16x16x32_bf16 v[62:65], v[144:147], v[190:193], v[62:65]
	v_mfma_f32_16x16x32_bf16 v[58:61], v[166:169], v[190:193], v[58:61]
	v_mfma_f32_16x16x32_bf16 v[54:57], v[144:147], v[224:227], v[54:57]
	v_mfma_f32_16x16x32_bf16 v[50:53], v[166:169], v[224:227], v[50:53]
	v_mfma_f32_16x16x32_bf16 v[46:49], v[144:147], v[232:235], v[46:49]
	v_mfma_f32_16x16x32_bf16 v[42:45], v[166:169], v[232:235], v[42:45]
	v_mfma_f32_16x16x32_bf16 v[38:41], v[144:147], v[240:243], v[38:41]
	v_mfma_f32_16x16x32_bf16 v[34:37], v[166:169], v[240:243], v[34:37]
	v_mfma_f32_16x16x32_bf16 v[30:33], v[170:173], v[186:189], v[30:33]
	v_mfma_f32_16x16x32_bf16 v[26:29], v[178:181], v[186:189], v[26:29]
	v_mfma_f32_16x16x32_bf16 v[22:25], v[170:173], v[194:197], v[22:25]
	v_mfma_f32_16x16x32_bf16 v[18:21], v[178:181], v[194:197], v[18:21]
	v_mfma_f32_16x16x32_bf16 v[14:17], v[170:173], v[228:231], v[14:17]
	v_mfma_f32_16x16x32_bf16 v[10:13], v[178:181], v[228:231], v[10:13]
	v_mfma_f32_16x16x32_bf16 v[6:9], v[170:173], v[236:239], v[6:9]
	v_mfma_f32_16x16x32_bf16 v[2:5], v[178:181], v[236:239], v[2:5]
	v_mfma_f32_16x16x32_bf16 v[30:33], v[174:177], v[190:193], v[30:33]
	v_mfma_f32_16x16x32_bf16 v[26:29], v[182:185], v[190:193], v[26:29]
	v_mfma_f32_16x16x32_bf16 v[22:25], v[174:177], v[224:227], v[22:25]
	v_mfma_f32_16x16x32_bf16 v[18:21], v[182:185], v[224:227], v[18:21]
	v_mfma_f32_16x16x32_bf16 v[14:17], v[174:177], v[232:235], v[14:17]
	v_mfma_f32_16x16x32_bf16 v[10:13], v[182:185], v[232:235], v[10:13]
	v_mfma_f32_16x16x32_bf16 v[6:9], v[174:177], v[240:243], v[6:9]
	v_mfma_f32_16x16x32_bf16 v[2:5], v[182:185], v[240:243], v[2:5]
	s_barrier
	s_setprio 0
	s_add_i32 s27, 0, 0x18000
	v_add_u32_e32 v161, s27, v151
	s_add_i32 s33, 0, 0x1c000
	ds_read_b128 v[140:143], v161
	ds_read_b128 v[144:147], v161 offset:1024
	ds_read_b128 v[162:165], v161 offset:2048
	ds_read_b128 v[166:169], v161 offset:3072
	v_add_u32_e32 v161, s33, v151
	ds_read_b128 v[170:173], v161
	ds_read_b128 v[174:177], v161 offset:1024
	ds_read_b128 v[178:181], v161 offset:2048
	ds_read_b128 v[182:185], v161 offset:3072
	s_add_u32 s16, s16, 0x40000
	s_addc_u32 s17, s17, 0
	s_mov_b32 m0, s29
	v_lshl_add_u64 v[248:249], s[16:17], 0, v[134:135]
	ds_read_b128 v[186:189], v160 offset:32768
	ds_read_b128 v[190:193], v160 offset:33792
	ds_read_b128 v[194:197], v160 offset:34816
	ds_read_b128 v[224:227], v160 offset:35840
	ds_read_b128 v[228:231], v160 offset:36864
	ds_read_b128 v[232:235], v160 offset:37888
	ds_read_b128 v[236:239], v160 offset:38912
	ds_read_b128 v[240:243], v160 offset:39936
	global_load_lds_dwordx4 v[248:249], off
	v_lshl_add_u64 v[248:249], s[16:17], 0, v[132:133]
	s_mov_b32 m0, s36
	s_nop 0
	global_load_lds_dwordx4 v[248:249], off
	s_waitcnt vmcnt(8)
	s_waitcnt lgkmcnt(0)
	s_setprio 1
	s_barrier
	v_mfma_f32_16x16x32_bf16 v[126:129], v[140:143], v[186:189], v[126:129]
	v_mfma_f32_16x16x32_bf16 v[122:125], v[162:165], v[186:189], v[122:125]
	v_mfma_f32_16x16x32_bf16 v[118:121], v[140:143], v[194:197], v[118:121]
	v_mfma_f32_16x16x32_bf16 v[114:117], v[162:165], v[194:197], v[114:117]
	v_mfma_f32_16x16x32_bf16 v[110:113], v[140:143], v[228:231], v[110:113]
	v_mfma_f32_16x16x32_bf16 v[106:109], v[162:165], v[228:231], v[106:109]
	v_mfma_f32_16x16x32_bf16 v[102:105], v[140:143], v[236:239], v[102:105]
	v_mfma_f32_16x16x32_bf16 v[98:101], v[162:165], v[236:239], v[98:101]
	v_mfma_f32_16x16x32_bf16 v[126:129], v[144:147], v[190:193], v[126:129]
	v_mfma_f32_16x16x32_bf16 v[122:125], v[166:169], v[190:193], v[122:125]
	v_mfma_f32_16x16x32_bf16 v[118:121], v[144:147], v[224:227], v[118:121]
	v_mfma_f32_16x16x32_bf16 v[114:117], v[166:169], v[224:227], v[114:117]
	v_mfma_f32_16x16x32_bf16 v[110:113], v[144:147], v[232:235], v[110:113]
	v_mfma_f32_16x16x32_bf16 v[106:109], v[166:169], v[232:235], v[106:109]
	v_mfma_f32_16x16x32_bf16 v[102:105], v[144:147], v[240:243], v[102:105]
	v_mfma_f32_16x16x32_bf16 v[98:101], v[166:169], v[240:243], v[98:101]
	v_mfma_f32_16x16x32_bf16 v[94:97], v[170:173], v[186:189], v[94:97]
	v_mfma_f32_16x16x32_bf16 v[90:93], v[178:181], v[186:189], v[90:93]
	v_mfma_f32_16x16x32_bf16 v[86:89], v[170:173], v[194:197], v[86:89]
	v_mfma_f32_16x16x32_bf16 v[82:85], v[178:181], v[194:197], v[82:85]
	v_mfma_f32_16x16x32_bf16 v[78:81], v[170:173], v[228:231], v[78:81]
	v_mfma_f32_16x16x32_bf16 v[74:77], v[178:181], v[228:231], v[74:77]
	v_mfma_f32_16x16x32_bf16 v[70:73], v[170:173], v[236:239], v[70:73]
	v_mfma_f32_16x16x32_bf16 v[66:69], v[178:181], v[236:239], v[66:69]
	v_mfma_f32_16x16x32_bf16 v[94:97], v[174:177], v[190:193], v[94:97]
	v_mfma_f32_16x16x32_bf16 v[90:93], v[182:185], v[190:193], v[90:93]
	v_mfma_f32_16x16x32_bf16 v[86:89], v[174:177], v[224:227], v[86:89]
	v_mfma_f32_16x16x32_bf16 v[82:85], v[182:185], v[224:227], v[82:85]
	v_mfma_f32_16x16x32_bf16 v[78:81], v[174:177], v[232:235], v[78:81]
	v_mfma_f32_16x16x32_bf16 v[74:77], v[182:185], v[232:235], v[74:77]
	v_mfma_f32_16x16x32_bf16 v[70:73], v[174:177], v[240:243], v[70:73]
	v_mfma_f32_16x16x32_bf16 v[66:69], v[182:185], v[240:243], v[66:69]
	s_barrier
	s_setprio 0
	s_add_i32 s16, s27, s20
	v_lshl_add_u64 v[148:149], v[148:149], 0, s[30:31]
	s_mov_b32 m0, s16
	ds_read_b128 v[186:189], v160 offset:49152
	ds_read_b128 v[190:193], v160 offset:50176
	ds_read_b128 v[194:197], v160 offset:51200
	ds_read_b128 v[224:227], v160 offset:52224
	ds_read_b128 v[228:231], v160 offset:53248
	ds_read_b128 v[232:235], v160 offset:54272
	ds_read_b128 v[236:239], v160 offset:55296
	ds_read_b128 v[240:243], v160 offset:56320
	global_load_lds_dwordx4 v[148:149], off
	s_add_i32 m0, s16, 0x2000
	s_add_u32 s14, s14, 0x40080
	v_lshl_add_u64 v[148:149], v[198:199], 0, s[30:31]
	s_addc_u32 s15, s15, 0
	s_add_i32 s16, s33, s20
	global_load_lds_dwordx4 v[148:149], off
	v_lshl_add_u64 v[148:149], s[14:15], 0, v[0:1]
	s_mov_b32 m0, s16
	s_nop 0
	global_load_lds_dwordx4 v[148:149], off
	v_lshl_add_u64 v[148:149], s[14:15], 0, v[130:131]
	s_add_i32 m0, s16, 0x2000
	s_nop 0
	global_load_lds_dwordx4 v[148:149], off
	v_lshl_add_u64 v[148:149], v[244:245], 0, s[30:31]
	s_mov_b32 m0, s37
	s_nop 0
	global_load_lds_dwordx4 v[148:149], off
	v_lshl_add_u64 v[148:149], v[246:247], 0, s[30:31]
	s_mov_b32 m0, s44
	s_nop 0
	global_load_lds_dwordx4 v[148:149], off
	s_waitcnt vmcnt(8)
	s_waitcnt lgkmcnt(0)
	s_setprio 1
	s_barrier
	v_mfma_f32_16x16x32_bf16 v[62:65], v[140:143], v[186:189], v[62:65]
	v_mfma_f32_16x16x32_bf16 v[58:61], v[162:165], v[186:189], v[58:61]
	v_mfma_f32_16x16x32_bf16 v[54:57], v[140:143], v[194:197], v[54:57]
	v_mfma_f32_16x16x32_bf16 v[50:53], v[162:165], v[194:197], v[50:53]
	v_mfma_f32_16x16x32_bf16 v[46:49], v[140:143], v[228:231], v[46:49]
	v_mfma_f32_16x16x32_bf16 v[42:45], v[162:165], v[228:231], v[42:45]
	v_mfma_f32_16x16x32_bf16 v[38:41], v[140:143], v[236:239], v[38:41]
	v_mfma_f32_16x16x32_bf16 v[34:37], v[162:165], v[236:239], v[34:37]
	v_mfma_f32_16x16x32_bf16 v[62:65], v[144:147], v[190:193], v[62:65]
	v_mfma_f32_16x16x32_bf16 v[58:61], v[166:169], v[190:193], v[58:61]
	v_mfma_f32_16x16x32_bf16 v[54:57], v[144:147], v[224:227], v[54:57]
	v_mfma_f32_16x16x32_bf16 v[50:53], v[166:169], v[224:227], v[50:53]
	v_mfma_f32_16x16x32_bf16 v[46:49], v[144:147], v[232:235], v[46:49]
	v_mfma_f32_16x16x32_bf16 v[42:45], v[166:169], v[232:235], v[42:45]
	v_mfma_f32_16x16x32_bf16 v[38:41], v[144:147], v[240:243], v[38:41]
	v_mfma_f32_16x16x32_bf16 v[34:37], v[166:169], v[240:243], v[34:37]
	v_mfma_f32_16x16x32_bf16 v[30:33], v[170:173], v[186:189], v[30:33]
	v_mfma_f32_16x16x32_bf16 v[26:29], v[178:181], v[186:189], v[26:29]
	v_mfma_f32_16x16x32_bf16 v[22:25], v[170:173], v[194:197], v[22:25]
	v_mfma_f32_16x16x32_bf16 v[18:21], v[178:181], v[194:197], v[18:21]
	v_mfma_f32_16x16x32_bf16 v[14:17], v[170:173], v[228:231], v[14:17]
	v_mfma_f32_16x16x32_bf16 v[10:13], v[178:181], v[228:231], v[10:13]
	v_mfma_f32_16x16x32_bf16 v[6:9], v[170:173], v[236:239], v[6:9]
	v_mfma_f32_16x16x32_bf16 v[2:5], v[178:181], v[236:239], v[2:5]
	v_mfma_f32_16x16x32_bf16 v[30:33], v[174:177], v[190:193], v[30:33]
	v_mfma_f32_16x16x32_bf16 v[26:29], v[182:185], v[190:193], v[26:29]
	v_mfma_f32_16x16x32_bf16 v[22:25], v[174:177], v[224:227], v[22:25]
	v_mfma_f32_16x16x32_bf16 v[18:21], v[182:185], v[224:227], v[18:21]
	v_mfma_f32_16x16x32_bf16 v[14:17], v[174:177], v[232:235], v[14:17]
	v_mfma_f32_16x16x32_bf16 v[10:13], v[182:185], v[232:235], v[10:13]
	v_mfma_f32_16x16x32_bf16 v[6:9], v[174:177], v[240:243], v[6:9]
	v_mfma_f32_16x16x32_bf16 v[2:5], v[182:185], v[240:243], v[2:5]
	s_barrier
	s_setprio 0
	s_add_i32 s51, s51, 2
	s_add_u32 s2, s2, 0x100
	s_addc_u32 s3, s3, 0
	s_add_u32 s49, s49, 0x100
	s_addc_u32 s50, s50, 0
	s_cmp_gt_u32 s51, 13
	s_cbranch_scc0 .LBB0_922
	s_and_b64 vcc, exec, s[4:5]
	s_cbranch_vccz .LBB0_925
	s_barrier

.LBB0_1060:
	s_add_u32 s18, s2, 0xfff80080
	s_addc_u32 s19, s3, -1
	s_add_i32 s27, 0, 0x10000
	s_cmp_eq_u32 s51, 28
	s_cselect_b32 s21, s13, s19
	s_cselect_b32 s20, s41, s18
	s_cselect_b32 s19, s11, s50
	s_cselect_b32 s18, s48, s49
	s_add_i32 s33, 0, 0x14000
	v_add_u32_e32 v156, s27, v153
	v_add_u32_e32 v172, s33, v153
	ds_read_b128 v[140:143], v156
	ds_read_b128 v[144:147], v156 offset:1024
	ds_read_b128 v[148:151], v156 offset:2048
	ds_read_b128 v[156:159], v156 offset:3072
	ds_read_b128 v[160:163], v172
	ds_read_b128 v[164:167], v172 offset:1024
	ds_read_b128 v[168:171], v172 offset:2048
	ds_read_b128 v[172:175], v172 offset:3072
	v_lshl_add_u64 v[232:233], s[2:3], 0, v[136:137]
	s_add_i32 m0, s37, 0xc000
	ds_read_b128 v[176:179], v155
	ds_read_b128 v[180:183], v155 offset:1024
	ds_read_b128 v[184:187], v155 offset:2048
	ds_read_b128 v[188:191], v155 offset:3072
	ds_read_b128 v[192:195], v155 offset:4096
	ds_read_b128 v[196:199], v155 offset:5120
	ds_read_b128 v[224:227], v155 offset:6144
	ds_read_b128 v[228:231], v155 offset:7168
	global_load_lds_dwordx4 v[232:233], off
	v_lshl_add_u64 v[232:233], s[2:3], 0, v[138:139]
	s_add_i32 m0, s37, 0xe000
	s_nop 0
	global_load_lds_dwordx4 v[232:233], off
	s_waitcnt vmcnt(8)
	s_waitcnt lgkmcnt(0)
	s_setprio 1
	s_barrier
	v_mfma_f32_16x16x32_bf16 v[126:129], v[140:143], v[176:179], v[126:129]
	v_mfma_f32_16x16x32_bf16 v[122:125], v[148:151], v[176:179], v[122:125]
	v_mfma_f32_16x16x32_bf16 v[110:113], v[140:143], v[184:187], v[110:113]
	v_mfma_f32_16x16x32_bf16 v[106:109], v[148:151], v[184:187], v[106:109]
	v_mfma_f32_16x16x32_bf16 v[94:97], v[140:143], v[192:195], v[94:97]
	v_mfma_f32_16x16x32_bf16 v[90:93], v[148:151], v[192:195], v[90:93]
	v_mfma_f32_16x16x32_bf16 v[78:81], v[140:143], v[224:227], v[78:81]
	v_mfma_f32_16x16x32_bf16 v[74:77], v[148:151], v[224:227], v[74:77]
	v_mfma_f32_16x16x32_bf16 v[126:129], v[144:147], v[180:183], v[126:129]
	v_mfma_f32_16x16x32_bf16 v[122:125], v[156:159], v[180:183], v[122:125]
	v_mfma_f32_16x16x32_bf16 v[110:113], v[144:147], v[188:191], v[110:113]
	v_mfma_f32_16x16x32_bf16 v[106:109], v[156:159], v[188:191], v[106:109]
	v_mfma_f32_16x16x32_bf16 v[94:97], v[144:147], v[196:199], v[94:97]
	v_mfma_f32_16x16x32_bf16 v[90:93], v[156:159], v[196:199], v[90:93]
	v_mfma_f32_16x16x32_bf16 v[78:81], v[144:147], v[228:231], v[78:81]
	v_mfma_f32_16x16x32_bf16 v[74:77], v[156:159], v[228:231], v[74:77]
	v_mfma_f32_16x16x32_bf16 v[118:121], v[160:163], v[176:179], v[118:121]
	v_mfma_f32_16x16x32_bf16 v[114:117], v[168:171], v[176:179], v[114:117]
	v_mfma_f32_16x16x32_bf16 v[102:105], v[160:163], v[184:187], v[102:105]
	v_mfma_f32_16x16x32_bf16 v[98:101], v[168:171], v[184:187], v[98:101]
	v_mfma_f32_16x16x32_bf16 v[86:89], v[160:163], v[192:195], v[86:89]
	v_mfma_f32_16x16x32_bf16 v[82:85], v[168:171], v[192:195], v[82:85]
	v_mfma_f32_16x16x32_bf16 v[70:73], v[160:163], v[224:227], v[70:73]
	v_mfma_f32_16x16x32_bf16 v[66:69], v[168:171], v[224:227], v[66:69]
	v_mfma_f32_16x16x32_bf16 v[118:121], v[164:167], v[180:183], v[118:121]
	v_mfma_f32_16x16x32_bf16 v[114:117], v[172:175], v[180:183], v[114:117]
	v_mfma_f32_16x16x32_bf16 v[102:105], v[164:167], v[188:191], v[102:105]
	v_mfma_f32_16x16x32_bf16 v[98:101], v[172:175], v[188:191], v[98:101]
	v_mfma_f32_16x16x32_bf16 v[86:89], v[164:167], v[196:199], v[86:89]
	v_mfma_f32_16x16x32_bf16 v[82:85], v[172:175], v[196:199], v[82:85]
	v_mfma_f32_16x16x32_bf16 v[70:73], v[164:167], v[228:231], v[70:73]
	v_mfma_f32_16x16x32_bf16 v[66:69], v[172:175], v[228:231], v[66:69]
	s_barrier
	s_setprio 0
	s_add_i32 s27, s27, s36
	v_lshl_add_u64 v[232:233], s[18:19], 0, v[0:1]
	s_mov_b32 m0, s27
	ds_read_b128 v[176:179], v155 offset:16384
	ds_read_b128 v[180:183], v155 offset:17408
	ds_read_b128 v[184:187], v155 offset:18432
	ds_read_b128 v[188:191], v155 offset:19456
	ds_read_b128 v[192:195], v155 offset:20480
	ds_read_b128 v[196:199], v155 offset:21504
	ds_read_b128 v[224:227], v155 offset:22528
	ds_read_b128 v[228:231], v155 offset:23552
	global_load_lds_dwordx4 v[232:233], off
	s_add_i32 m0, s27, 0x2000
	s_add_u32 s52, s18, 0x80000
	v_lshl_add_u64 v[234:235], s[18:19], 0, v[130:131]
	s_addc_u32 s53, s19, 0
	s_add_i32 s27, s33, s36
	global_load_lds_dwordx4 v[234:235], off
	v_lshl_add_u64 v[236:237], s[52:53], 0, v[0:1]
	s_mov_b32 m0, s27
	v_lshl_add_u64 v[238:239], s[20:21], 0, v[132:133]
	global_load_lds_dwordx4 v[236:237], off
	v_lshl_add_u64 v[236:237], s[52:53], 0, v[130:131]
	s_add_i32 m0, s27, 0x2000
	s_nop 0
	global_load_lds_dwordx4 v[236:237], off
	v_lshl_add_u64 v[236:237], s[20:21], 0, v[134:135]
	s_mov_b32 m0, s37
	s_nop 0
	global_load_lds_dwordx4 v[236:237], off
	s_mov_b32 m0, s42
	s_nop 0
	global_load_lds_dwordx4 v[238:239], off
	s_waitcnt vmcnt(8)
	s_waitcnt lgkmcnt(0)
	s_setprio 1
	s_barrier
	v_mfma_f32_16x16x32_bf16 v[62:65], v[140:143], v[176:179], v[62:65]
	v_mfma_f32_16x16x32_bf16 v[58:61], v[148:151], v[176:179], v[58:61]
	v_mfma_f32_16x16x32_bf16 v[46:49], v[140:143], v[184:187], v[46:49]
	v_mfma_f32_16x16x32_bf16 v[42:45], v[148:151], v[184:187], v[42:45]
	v_mfma_f32_16x16x32_bf16 v[30:33], v[140:143], v[192:195], v[30:33]
	v_mfma_f32_16x16x32_bf16 v[26:29], v[148:151], v[192:195], v[26:29]
	v_mfma_f32_16x16x32_bf16 v[14:17], v[140:143], v[224:227], v[14:17]
	v_mfma_f32_16x16x32_bf16 v[10:13], v[148:151], v[224:227], v[10:13]
	v_mfma_f32_16x16x32_bf16 v[62:65], v[144:147], v[180:183], v[62:65]
	v_mfma_f32_16x16x32_bf16 v[58:61], v[156:159], v[180:183], v[58:61]
	v_mfma_f32_16x16x32_bf16 v[46:49], v[144:147], v[188:191], v[46:49]
	v_mfma_f32_16x16x32_bf16 v[42:45], v[156:159], v[188:191], v[42:45]
	v_mfma_f32_16x16x32_bf16 v[30:33], v[144:147], v[196:199], v[30:33]
	v_mfma_f32_16x16x32_bf16 v[26:29], v[156:159], v[196:199], v[26:29]
	v_mfma_f32_16x16x32_bf16 v[14:17], v[144:147], v[228:231], v[14:17]
	v_mfma_f32_16x16x32_bf16 v[10:13], v[156:159], v[228:231], v[10:13]
	v_mfma_f32_16x16x32_bf16 v[54:57], v[160:163], v[176:179], v[54:57]
	v_mfma_f32_16x16x32_bf16 v[50:53], v[168:171], v[176:179], v[50:53]
	v_mfma_f32_16x16x32_bf16 v[38:41], v[160:163], v[184:187], v[38:41]
	v_mfma_f32_16x16x32_bf16 v[34:37], v[168:171], v[184:187], v[34:37]
	v_mfma_f32_16x16x32_bf16 v[22:25], v[160:163], v[192:195], v[22:25]
	v_mfma_f32_16x16x32_bf16 v[18:21], v[168:171], v[192:195], v[18:21]
	v_mfma_f32_16x16x32_bf16 v[6:9], v[160:163], v[224:227], v[6:9]
	v_mfma_f32_16x16x32_bf16 v[2:5], v[168:171], v[224:227], v[2:5]
	v_mfma_f32_16x16x32_bf16 v[54:57], v[164:167], v[180:183], v[54:57]
	v_mfma_f32_16x16x32_bf16 v[50:53], v[172:175], v[180:183], v[50:53]
	v_mfma_f32_16x16x32_bf16 v[38:41], v[164:167], v[188:191], v[38:41]
	v_mfma_f32_16x16x32_bf16 v[34:37], v[172:175], v[188:191], v[34:37]
	v_mfma_f32_16x16x32_bf16 v[22:25], v[164:167], v[196:199], v[22:25]
	v_mfma_f32_16x16x32_bf16 v[18:21], v[172:175], v[196:199], v[18:21]
	v_mfma_f32_16x16x32_bf16 v[6:9], v[164:167], v[228:231], v[6:9]
	v_mfma_f32_16x16x32_bf16 v[2:5], v[172:175], v[228:231], v[2:5]
	s_barrier
	s_setprio 0
	s_add_i32 s27, 0, 0x18000
	s_add_i32 s33, 0, 0x1c000
	v_add_u32_e32 v156, s27, v153
	v_add_u32_e32 v172, s33, v153
	ds_read_b128 v[140:143], v156
	ds_read_b128 v[144:147], v156 offset:1024
	ds_read_b128 v[148:151], v156 offset:2048
	ds_read_b128 v[156:159], v156 offset:3072
	ds_read_b128 v[160:163], v172
	ds_read_b128 v[164:167], v172 offset:1024
	ds_read_b128 v[168:171], v172 offset:2048
	ds_read_b128 v[172:175], v172 offset:3072
	s_add_u32 s20, s20, 0x80000
	s_addc_u32 s21, s21, 0
	s_mov_b32 m0, s43
	v_lshl_add_u64 v[240:241], s[20:21], 0, v[134:135]
	ds_read_b128 v[176:179], v155 offset:32768
	ds_read_b128 v[180:183], v155 offset:33792
	ds_read_b128 v[184:187], v155 offset:34816
	ds_read_b128 v[188:191], v155 offset:35840
	ds_read_b128 v[192:195], v155 offset:36864
	ds_read_b128 v[196:199], v155 offset:37888
	ds_read_b128 v[224:227], v155 offset:38912
	ds_read_b128 v[228:231], v155 offset:39936
	global_load_lds_dwordx4 v[240:241], off
	v_lshl_add_u64 v[240:241], s[20:21], 0, v[132:133]
	s_mov_b32 m0, s44
	s_nop 0
	global_load_lds_dwordx4 v[240:241], off
	s_waitcnt vmcnt(8)
	s_waitcnt lgkmcnt(0)
	s_setprio 1
	s_barrier
	v_mfma_f32_16x16x32_bf16 v[126:129], v[140:143], v[176:179], v[126:129]
	v_mfma_f32_16x16x32_bf16 v[122:125], v[148:151], v[176:179], v[122:125]
	v_mfma_f32_16x16x32_bf16 v[110:113], v[140:143], v[184:187], v[110:113]
	v_mfma_f32_16x16x32_bf16 v[106:109], v[148:151], v[184:187], v[106:109]
	v_mfma_f32_16x16x32_bf16 v[94:97], v[140:143], v[192:195], v[94:97]
	v_mfma_f32_16x16x32_bf16 v[90:93], v[148:151], v[192:195], v[90:93]
	v_mfma_f32_16x16x32_bf16 v[78:81], v[140:143], v[224:227], v[78:81]
	v_mfma_f32_16x16x32_bf16 v[74:77], v[148:151], v[224:227], v[74:77]
	v_mfma_f32_16x16x32_bf16 v[126:129], v[144:147], v[180:183], v[126:129]
	v_mfma_f32_16x16x32_bf16 v[122:125], v[156:159], v[180:183], v[122:125]
	v_mfma_f32_16x16x32_bf16 v[110:113], v[144:147], v[188:191], v[110:113]
	v_mfma_f32_16x16x32_bf16 v[106:109], v[156:159], v[188:191], v[106:109]
	v_mfma_f32_16x16x32_bf16 v[94:97], v[144:147], v[196:199], v[94:97]
	v_mfma_f32_16x16x32_bf16 v[90:93], v[156:159], v[196:199], v[90:93]
	v_mfma_f32_16x16x32_bf16 v[78:81], v[144:147], v[228:231], v[78:81]
	v_mfma_f32_16x16x32_bf16 v[74:77], v[156:159], v[228:231], v[74:77]
	v_mfma_f32_16x16x32_bf16 v[118:121], v[160:163], v[176:179], v[118:121]
	v_mfma_f32_16x16x32_bf16 v[114:117], v[168:171], v[176:179], v[114:117]
	v_mfma_f32_16x16x32_bf16 v[102:105], v[160:163], v[184:187], v[102:105]
	v_mfma_f32_16x16x32_bf16 v[98:101], v[168:171], v[184:187], v[98:101]
	v_mfma_f32_16x16x32_bf16 v[86:89], v[160:163], v[192:195], v[86:89]
	v_mfma_f32_16x16x32_bf16 v[82:85], v[168:171], v[192:195], v[82:85]
	v_mfma_f32_16x16x32_bf16 v[70:73], v[160:163], v[224:227], v[70:73]
	v_mfma_f32_16x16x32_bf16 v[66:69], v[168:171], v[224:227], v[66:69]
	v_mfma_f32_16x16x32_bf16 v[118:121], v[164:167], v[180:183], v[118:121]
	v_mfma_f32_16x16x32_bf16 v[114:117], v[172:175], v[180:183], v[114:117]
	v_mfma_f32_16x16x32_bf16 v[102:105], v[164:167], v[188:191], v[102:105]
	v_mfma_f32_16x16x32_bf16 v[98:101], v[172:175], v[188:191], v[98:101]
	v_mfma_f32_16x16x32_bf16 v[86:89], v[164:167], v[196:199], v[86:89]
	v_mfma_f32_16x16x32_bf16 v[82:85], v[172:175], v[196:199], v[82:85]
	v_mfma_f32_16x16x32_bf16 v[70:73], v[164:167], v[228:231], v[70:73]
	v_mfma_f32_16x16x32_bf16 v[66:69], v[172:175], v[228:231], v[66:69]
	s_barrier
	s_setprio 0
	s_add_i32 s20, s27, s36
	v_lshl_add_u64 v[232:233], v[232:233], 0, s[30:31]
	s_mov_b32 m0, s20
	ds_read_b128 v[176:179], v155 offset:49152
	ds_read_b128 v[180:183], v155 offset:50176
	ds_read_b128 v[184:187], v155 offset:51200
	ds_read_b128 v[188:191], v155 offset:52224
	ds_read_b128 v[192:195], v155 offset:53248
	ds_read_b128 v[196:199], v155 offset:54272
	ds_read_b128 v[224:227], v155 offset:55296
	ds_read_b128 v[228:231], v155 offset:56320
	global_load_lds_dwordx4 v[232:233], off
	s_add_i32 m0, s20, 0x2000
	s_add_u32 s18, s18, 0x80080
	v_lshl_add_u64 v[232:233], v[234:235], 0, s[30:31]
	s_addc_u32 s19, s19, 0
	s_add_i32 s20, s33, s36
	global_load_lds_dwordx4 v[232:233], off
	v_lshl_add_u64 v[232:233], s[18:19], 0, v[0:1]
	s_mov_b32 m0, s20
	s_nop 0
	global_load_lds_dwordx4 v[232:233], off
	v_lshl_add_u64 v[232:233], s[18:19], 0, v[130:131]
	s_add_i32 m0, s20, 0x2000
	s_nop 0
	global_load_lds_dwordx4 v[232:233], off
	v_lshl_add_u64 v[232:233], v[236:237], 0, s[30:31]
	s_mov_b32 m0, s45
	s_nop 0
	global_load_lds_dwordx4 v[232:233], off
	v_lshl_add_u64 v[232:233], v[238:239], 0, s[30:31]
	s_mov_b32 m0, s46
	s_nop 0
	global_load_lds_dwordx4 v[232:233], off
	s_waitcnt vmcnt(8)
	s_waitcnt lgkmcnt(0)
	s_setprio 1
	s_barrier
	v_mfma_f32_16x16x32_bf16 v[62:65], v[140:143], v[176:179], v[62:65]
	v_mfma_f32_16x16x32_bf16 v[58:61], v[148:151], v[176:179], v[58:61]
	v_mfma_f32_16x16x32_bf16 v[46:49], v[140:143], v[184:187], v[46:49]
	v_mfma_f32_16x16x32_bf16 v[42:45], v[148:151], v[184:187], v[42:45]
	v_mfma_f32_16x16x32_bf16 v[30:33], v[140:143], v[192:195], v[30:33]
	v_mfma_f32_16x16x32_bf16 v[26:29], v[148:151], v[192:195], v[26:29]
	v_mfma_f32_16x16x32_bf16 v[14:17], v[140:143], v[224:227], v[14:17]
	v_mfma_f32_16x16x32_bf16 v[10:13], v[148:151], v[224:227], v[10:13]
	v_mfma_f32_16x16x32_bf16 v[62:65], v[144:147], v[180:183], v[62:65]
	v_mfma_f32_16x16x32_bf16 v[58:61], v[156:159], v[180:183], v[58:61]
	v_mfma_f32_16x16x32_bf16 v[46:49], v[144:147], v[188:191], v[46:49]
	v_mfma_f32_16x16x32_bf16 v[42:45], v[156:159], v[188:191], v[42:45]
	v_mfma_f32_16x16x32_bf16 v[30:33], v[144:147], v[196:199], v[30:33]
	v_mfma_f32_16x16x32_bf16 v[26:29], v[156:159], v[196:199], v[26:29]
	v_mfma_f32_16x16x32_bf16 v[14:17], v[144:147], v[228:231], v[14:17]
	v_mfma_f32_16x16x32_bf16 v[10:13], v[156:159], v[228:231], v[10:13]
	v_mfma_f32_16x16x32_bf16 v[54:57], v[160:163], v[176:179], v[54:57]
	v_mfma_f32_16x16x32_bf16 v[50:53], v[168:171], v[176:179], v[50:53]
	v_mfma_f32_16x16x32_bf16 v[38:41], v[160:163], v[184:187], v[38:41]
	v_mfma_f32_16x16x32_bf16 v[34:37], v[168:171], v[184:187], v[34:37]
	v_mfma_f32_16x16x32_bf16 v[22:25], v[160:163], v[192:195], v[22:25]
	v_mfma_f32_16x16x32_bf16 v[18:21], v[168:171], v[192:195], v[18:21]
	v_mfma_f32_16x16x32_bf16 v[6:9], v[160:163], v[224:227], v[6:9]
	v_mfma_f32_16x16x32_bf16 v[2:5], v[168:171], v[224:227], v[2:5]
	v_mfma_f32_16x16x32_bf16 v[54:57], v[164:167], v[180:183], v[54:57]
	v_mfma_f32_16x16x32_bf16 v[50:53], v[172:175], v[180:183], v[50:53]
	v_mfma_f32_16x16x32_bf16 v[38:41], v[164:167], v[188:191], v[38:41]
	v_mfma_f32_16x16x32_bf16 v[34:37], v[172:175], v[188:191], v[34:37]
	v_mfma_f32_16x16x32_bf16 v[22:25], v[164:167], v[196:199], v[22:25]
	v_mfma_f32_16x16x32_bf16 v[18:21], v[172:175], v[196:199], v[18:21]
	v_mfma_f32_16x16x32_bf16 v[6:9], v[164:167], v[228:231], v[6:9]
	v_mfma_f32_16x16x32_bf16 v[2:5], v[172:175], v[228:231], v[2:5]
	s_barrier
	s_setprio 0
	s_add_i32 s51, s51, 2
	s_add_u32 s2, s2, 0x100
	s_addc_u32 s3, s3, 0
	s_add_u32 s49, s49, 0x100
	s_addc_u32 s50, s50, 0
	s_cmp_gt_u32 s51, 29
	s_cbranch_scc0 .LBB0_1060
	s_and_b64 vcc, exec, s[8:9]
	s_cbranch_vccz .LBB0_1063
	s_barrier
